# P8 panel exchange: the acquire invalidate is issued before the panel-counter spin as well (on top of the grid-barrier invalidate hoist)
# speedup vs baseline: 1.0081x; 1.0013x over previous
;     __device__ __forceinline__ void operator()(EPI_ARGS) const {
;     ...
;         if (threadIdx.x == 0) {
;             __builtin_amdgcn_fence(__ATOMIC_RELEASE, "agent");
;             __hip_atomic_fetch_add(cnt + u.pm, 1u, __ATOMIC_RELAXED, __HIP_MEMORY_SCOPE_AGENT);
;             unsigned sp = 0;
;             while (__hip_atomic_load(cnt + u.pm, __ATOMIC_RELAXED, __HIP_MEMORY_SCOPE_AGENT) < 8u) { __builtin_amdgcn_s_sleep(1); if (++sp > (1u << 22)) break; }
;             __builtin_amdgcn_fence(__ATOMIC_ACQUIRE, "agent");
.LBB0_1325:
	s_or_b64 exec, exec, s[26:27]
	buffer_inv sc1
	s_mov_b32 s7, 0x400001
	s_branch .LBB0_1327

; #define FOR_AI_M _Pragma("unroll") for (int ai = 0; ai < 2; ++ai) _Pragma("unroll") for (int m = 0; m < 4; ++m)
; #define FOR_BJ_N _Pragma("unroll") for (int bj = 0; bj < 2; ++bj) _Pragma("unroll") for (int n = 0; n < 2; ++n)
;     __device__ __forceinline__ void operator()(EPI_ARGS) const {
;     ...
;             while (__hip_atomic_load(cnt + u.pm, __ATOMIC_RELAXED, __HIP_MEMORY_SCOPE_AGENT) < 8u) { __builtin_amdgcn_s_sleep(1); if (++sp > (1u << 22)) break; }
;             __builtin_amdgcn_fence(__ATOMIC_ACQUIRE, "agent");
;             asm volatile("s_waitcnt vmcnt(0)" ::: "memory");
;         }
;         __builtin_amdgcn_s_barrier(); asm volatile("" ::: "memory");
;         f32x4 gv[2][2];
; #pragma unroll
;         for (int bj = 0; bj < 2; ++bj)
; #pragma unroll
;             for (int n = 0; n < 2; ++n) gv[bj][n] = *(const f32x4*)(gain + u.pn * 256 + bj * 128 + wc * 32 + n * 16 + 4 * fq);
;         FOR_AI_M {
;             const int row = u.pm * 256 + ai * 128 + wr * 64 + m * 16 + fr;
;             const float rs = rsqrtf(__hip_atomic_load(ssq_o + row, __ATOMIC_RELAXED, __HIP_MEMORY_SCOPE_AGENT) * (1.0f / 2048.0f) + EPS);
;             FOR_BJ_N { const int col = u.pn * 256 + bj * 128 + wc * 32 + n * 16 + 4 * fq;
;                 __builtin_nontemporal_store(acc[ai][bj][m][n] * rs * gv[bj][n], (f32x4*)(out + ((size_t)row * 2048 + col))); }
.LBB0_1327:
	global_load_dword v0, v129, s[10:11] sc1
	s_mov_b64 s[12:13], -1
	s_waitcnt vmcnt(0)
	v_cmp_lt_u32_e32 vcc, 7, v0
	s_cbranch_vccnz .LBB0_1326
	s_sleep 1
	global_load_dword v0, v129, s[10:11] sc1
	s_waitcnt vmcnt(0)
	v_cmp_gt_u32_e32 vcc, 8, v0
	s_cbranch_vccz .LBB0_1326
	s_sleep 1
	global_load_dword v0, v129, s[10:11] sc1
	s_waitcnt vmcnt(0)
	v_cmp_gt_u32_e32 vcc, 8, v0
	s_cbranch_vccz .LBB0_1326
	s_sleep 1
	global_load_dword v0, v129, s[10:11] sc1
	s_waitcnt vmcnt(0)
	v_cmp_gt_u32_e32 vcc, 8, v0
	s_cbranch_vccz .LBB0_1326
	s_sleep 1
	global_load_dword v0, v129, s[10:11] sc1
	s_waitcnt vmcnt(0)
	v_cmp_gt_u32_e32 vcc, 8, v0
	s_cbranch_vccz .LBB0_1326
	s_add_i32 s7, s7, -5
	s_cmp_eq_u32 s7, 0
	s_cselect_b64 s[12:13], -1, 0
	s_sleep 1
	s_branch .LBB0_1326
.LBB0_1333:
	s_waitcnt vmcnt(0)
.LBB0_1334:
	s_or_b64 exec, exec, s[8:9]
	s_ashr_i32 s7, s6, 31
	s_lshl_b64 s[6:7], s[6:7], 2
	s_add_u32 s6, s44, s6
	s_addc_u32 s7, s45, s7
	v_ashrrev_i32_e32 v141, 31, v140
	s_barrier
	s_waitcnt lgkmcnt(0)
	v_lshl_add_u64 v[0:1], v[140:141], 2, s[6:7]
	v_lshl_add_u64 v[140:141], v[138:139], 2, s[4:5]
	global_load_dwordx4 v[12:15], v[0:1], off
	global_load_dwordx4 v[8:11], v[0:1], off offset:64
	global_load_dwordx4 v[4:7], v[0:1], off offset:512
	s_nop 0
	global_load_dwordx4 v[0:3], v[0:1], off offset:576
	v_lshlrev_b64 v[192:193], 13, v[138:139]
	global_load_dword v140, v[140:141], off sc1
	v_add_u32_e32 v184, 16, v136
	v_ashrrev_i32_e32 v185, 31, v184
	v_add_u32_e32 v186, 0x80, v136
	v_add_u32_e32 v188, 0x90, v136
	v_ashrrev_i32_e32 v187, 31, v186
	v_ashrrev_i32_e32 v189, 31, v188
	s_mov_b64 s[6:7], -1
	s_waitcnt vmcnt(0)
	v_fmamk_f32 v140, v140, 0x3a000000, v182
	v_cmp_gt_f32_e32 vcc, s47, v140
	v_mul_f32_e32 v141, 0x4b800000, v140
	s_nop 0
	v_cndmask_b32_e32 v140, v140, v141, vcc
	v_rsq_f32_e32 v140, v140
	s_nop 0
	v_mul_f32_e32 v141, 0x45800000, v140
	v_cndmask_b32_e32 v190, v140, v141, vcc
	v_pk_mul_f32 v[124:125], v[124:125], v[190:191] op_sel_hi:[1,0]
	v_pk_mul_f32 v[126:127], v[126:127], v[190:191] op_sel_hi:[1,0]
	v_pk_mul_f32 v[138:139], v[12:13], v[124:125]
	v_pk_mul_f32 v[140:141], v[14:15], v[126:127]
	v_lshl_add_u64 v[126:127], s[86:87], 0, v[192:193]
	v_lshlrev_b64 v[124:125], 2, v[136:137]
	v_lshl_add_u64 v[136:137], v[126:127], 0, v[124:125]
	v_pk_mul_f32 v[120:121], v[120:121], v[190:191] op_sel_hi:[1,0]
	global_store_dwordx4 v[136:137], v[138:141], off
	v_pk_mul_f32 v[122:123], v[122:123], v[190:191] op_sel_hi:[1,0]
	v_pk_mul_f32 v[136:137], v[8:9], v[120:121]
	v_lshlrev_b64 v[120:121], 2, v[184:185]
	v_pk_mul_f32 v[138:139], v[10:11], v[122:123]
	v_lshl_add_u64 v[122:123], v[126:127], 0, v[120:121]
	v_pk_mul_f32 v[116:117], v[116:117], v[190:191] op_sel_hi:[1,0]
	global_store_dwordx4 v[122:123], v[136:139], off
	v_pk_mul_f32 v[118:119], v[118:119], v[190:191] op_sel_hi:[1,0]
	v_pk_mul_f32 v[114:115], v[114:115], v[190:191] op_sel_hi:[1,0]
	v_pk_mul_f32 v[136:137], v[4:5], v[116:117]
	v_lshlrev_b64 v[116:117], 2, v[186:187]
	v_pk_mul_f32 v[138:139], v[6:7], v[118:119]
	v_lshl_add_u64 v[118:119], v[126:127], 0, v[116:117]
	global_store_dwordx4 v[118:119], v[136:139], off
	v_pk_mul_f32 v[118:119], v[142:143], v[190:191] op_sel_hi:[1,0]
	s_nop 0
	v_pk_mul_f32 v[138:139], v[2:3], v[114:115]
	v_lshlrev_b64 v[114:115], 2, v[188:189]
	v_pk_mul_f32 v[136:137], v[0:1], v[118:119]
	v_lshl_add_u64 v[118:119], v[126:127], 0, v[114:115]
	global_store_dwordx4 v[118:119], v[136:139], off
	v_lshl_add_u64 v[118:119], v[112:113], 2, s[4:5]
	global_load_dword v118, v[118:119], off sc1
	v_lshlrev_b64 v[112:113], 13, v[112:113]
	v_lshl_add_u64 v[112:113], s[86:87], 0, v[112:113]
	v_lshl_add_u64 v[122:123], v[112:113], 0, v[124:125]
	s_waitcnt vmcnt(0)
	v_fmamk_f32 v118, v118, 0x3a000000, v182
	v_cmp_gt_f32_e32 vcc, s47, v118
	v_mul_f32_e32 v119, 0x4b800000, v118
	s_nop 0
	v_cndmask_b32_e32 v118, v118, v119, vcc
	v_rsq_f32_e32 v118, v118
	s_nop 0
	v_mul_f32_e32 v119, 0x45800000, v118
	v_cndmask_b32_e32 v118, v118, v119, vcc
	v_pk_mul_f32 v[108:109], v[108:109], v[118:119] op_sel_hi:[1,0]
	v_pk_mul_f32 v[110:111], v[110:111], v[118:119] op_sel_hi:[1,0]
	v_pk_mul_f32 v[108:109], v[12:13], v[108:109]
	v_pk_mul_f32 v[110:111], v[14:15], v[110:111]
	v_pk_mul_f32 v[104:105], v[104:105], v[118:119] op_sel_hi:[1,0]
	v_pk_mul_f32 v[106:107], v[106:107], v[118:119] op_sel_hi:[1,0]
	global_store_dwordx4 v[122:123], v[108:111], off
	v_pk_mul_f32 v[106:107], v[10:11], v[106:107]
	v_pk_mul_f32 v[104:105], v[8:9], v[104:105]
	v_lshl_add_u64 v[108:109], v[112:113], 0, v[120:121]
	v_pk_mul_f32 v[100:101], v[100:101], v[118:119] op_sel_hi:[1,0]
	v_pk_mul_f32 v[102:103], v[102:103], v[118:119] op_sel_hi:[1,0]
	global_store_dwordx4 v[108:109], v[104:107], off
	v_pk_mul_f32 v[102:103], v[6:7], v[102:103]
	v_pk_mul_f32 v[100:101], v[4:5], v[100:101]
	v_lshl_add_u64 v[104:105], v[112:113], 0, v[116:117]
	global_store_dwordx4 v[104:105], v[100:103], off
	v_pk_mul_f32 v[98:99], v[98:99], v[118:119] op_sel_hi:[1,0]
	s_nop 0
	v_pk_mul_f32 v[102:103], v[144:145], v[118:119] op_sel_hi:[1,0]
	v_pk_mul_f32 v[100:101], v[2:3], v[98:99]
	v_pk_mul_f32 v[98:99], v[0:1], v[102:103]
	v_lshl_add_u64 v[102:103], v[112:113], 0, v[114:115]
	global_store_dwordx4 v[102:103], v[98:101], off
	s_nop 1
	v_lshl_add_u64 v[98:99], v[96:97], 2, s[4:5]
	global_load_dword v98, v[98:99], off sc1
	v_lshlrev_b64 v[96:97], 13, v[96:97]
	v_lshl_add_u64 v[96:97], s[86:87], 0, v[96:97]
	v_lshl_add_u64 v[100:101], v[96:97], 0, v[124:125]
	s_waitcnt vmcnt(0)
; #define FOR_AI_M _Pragma("unroll") for (int ai = 0; ai < 2; ++ai) _Pragma("unroll") for (int m = 0; m < 4; ++m)
; #define FOR_BJ_N _Pragma("unroll") for (int bj = 0; bj < 2; ++bj) _Pragma("unroll") for (int n = 0; n < 2; ++n)
;     __device__ __forceinline__ void operator()(EPI_ARGS) const {
;     ...
;         FOR_AI_M {
;             const int row = u.pm * 256 + ai * 128 + wr * 64 + m * 16 + fr;
;             const float rs = rsqrtf(__hip_atomic_load(ssq_o + row, __ATOMIC_RELAXED, __HIP_MEMORY_SCOPE_AGENT) * (1.0f / 2048.0f) + EPS);
;             FOR_BJ_N { const int col = u.pn * 256 + bj * 128 + wc * 32 + n * 16 + 4 * fq;
;                 __builtin_nontemporal_store(acc[ai][bj][m][n] * rs * gv[bj][n], (f32x4*)(out + ((size_t)row * 2048 + col))); }
	v_fmamk_f32 v98, v98, 0x3a000000, v182
	v_cmp_gt_f32_e32 vcc, s47, v98
	v_mul_f32_e32 v99, 0x4b800000, v98
	s_nop 0
	v_cndmask_b32_e32 v98, v98, v99, vcc
	v_rsq_f32_e32 v98, v98
	s_nop 0
	v_mul_f32_e32 v99, 0x45800000, v98
	v_cndmask_b32_e32 v98, v98, v99, vcc
	v_pk_mul_f32 v[92:93], v[92:93], v[98:99] op_sel_hi:[1,0]
	v_pk_mul_f32 v[94:95], v[94:95], v[98:99] op_sel_hi:[1,0]
	v_pk_mul_f32 v[92:93], v[12:13], v[92:93]
	v_pk_mul_f32 v[94:95], v[14:15], v[94:95]
	v_pk_mul_f32 v[88:89], v[88:89], v[98:99] op_sel_hi:[1,0]
	v_pk_mul_f32 v[90:91], v[90:91], v[98:99] op_sel_hi:[1,0]
	global_store_dwordx4 v[100:101], v[92:95], off
	v_pk_mul_f32 v[90:91], v[10:11], v[90:91]
	v_pk_mul_f32 v[88:89], v[8:9], v[88:89]
	v_lshl_add_u64 v[92:93], v[96:97], 0, v[120:121]
	v_pk_mul_f32 v[84:85], v[84:85], v[98:99] op_sel_hi:[1,0]
	v_pk_mul_f32 v[86:87], v[86:87], v[98:99] op_sel_hi:[1,0]
	global_store_dwordx4 v[92:93], v[88:91], off
	v_pk_mul_f32 v[86:87], v[6:7], v[86:87]
	v_pk_mul_f32 v[84:85], v[4:5], v[84:85]
	v_lshl_add_u64 v[88:89], v[96:97], 0, v[116:117]
	global_store_dwordx4 v[88:89], v[84:87], off
	v_pk_mul_f32 v[82:83], v[82:83], v[98:99] op_sel_hi:[1,0]
	s_nop 0
	v_pk_mul_f32 v[86:87], v[146:147], v[98:99] op_sel_hi:[1,0]
	v_pk_mul_f32 v[84:85], v[2:3], v[82:83]
	v_pk_mul_f32 v[82:83], v[0:1], v[86:87]
	v_lshl_add_u64 v[86:87], v[96:97], 0, v[114:115]
	global_store_dwordx4 v[86:87], v[82:85], off
	s_nop 1
	v_lshl_add_u64 v[82:83], v[80:81], 2, s[4:5]
	global_load_dword v82, v[82:83], off sc1
	v_lshlrev_b64 v[80:81], 13, v[80:81]
	v_lshl_add_u64 v[80:81], s[86:87], 0, v[80:81]
	v_lshl_add_u64 v[84:85], v[80:81], 0, v[124:125]
	s_waitcnt vmcnt(0)
	v_fmamk_f32 v82, v82, 0x3a000000, v182
	v_cmp_gt_f32_e32 vcc, s47, v82
	v_mul_f32_e32 v83, 0x4b800000, v82
	s_nop 0
	v_cndmask_b32_e32 v82, v82, v83, vcc
	v_rsq_f32_e32 v82, v82
	s_nop 0
	v_mul_f32_e32 v83, 0x45800000, v82
	v_cndmask_b32_e32 v82, v82, v83, vcc
	v_pk_mul_f32 v[76:77], v[76:77], v[82:83] op_sel_hi:[1,0]
	v_pk_mul_f32 v[78:79], v[78:79], v[82:83] op_sel_hi:[1,0]
	v_pk_mul_f32 v[76:77], v[12:13], v[76:77]
	v_pk_mul_f32 v[78:79], v[14:15], v[78:79]
	v_pk_mul_f32 v[72:73], v[72:73], v[82:83] op_sel_hi:[1,0]
	v_pk_mul_f32 v[74:75], v[74:75], v[82:83] op_sel_hi:[1,0]
	global_store_dwordx4 v[84:85], v[76:79], off
	v_pk_mul_f32 v[74:75], v[10:11], v[74:75]
	v_pk_mul_f32 v[72:73], v[8:9], v[72:73]
	v_lshl_add_u64 v[76:77], v[80:81], 0, v[120:121]
	v_pk_mul_f32 v[68:69], v[68:69], v[82:83] op_sel_hi:[1,0]
	v_pk_mul_f32 v[70:71], v[70:71], v[82:83] op_sel_hi:[1,0]
	global_store_dwordx4 v[76:77], v[72:75], off
	v_pk_mul_f32 v[70:71], v[6:7], v[70:71]
	v_pk_mul_f32 v[68:69], v[4:5], v[68:69]
	v_lshl_add_u64 v[72:73], v[80:81], 0, v[116:117]
	global_store_dwordx4 v[72:73], v[68:71], off
	v_pk_mul_f32 v[66:67], v[66:67], v[82:83] op_sel_hi:[1,0]
	s_nop 0
	v_pk_mul_f32 v[70:71], v[148:149], v[82:83] op_sel_hi:[1,0]
	v_pk_mul_f32 v[68:69], v[2:3], v[66:67]
	v_pk_mul_f32 v[66:67], v[0:1], v[70:71]
	v_lshl_add_u64 v[70:71], v[80:81], 0, v[114:115]
	global_store_dwordx4 v[70:71], v[66:69], off
	s_nop 1
	v_lshl_add_u64 v[66:67], v[64:65], 2, s[4:5]
	global_load_dword v66, v[66:67], off sc1
	v_lshlrev_b64 v[64:65], 13, v[64:65]
	v_lshl_add_u64 v[64:65], s[86:87], 0, v[64:65]
	v_lshl_add_u64 v[68:69], v[64:65], 0, v[124:125]
	s_waitcnt vmcnt(0)
	v_fmamk_f32 v66, v66, 0x3a000000, v182
	v_cmp_gt_f32_e32 vcc, s47, v66
	v_mul_f32_e32 v67, 0x4b800000, v66
	s_nop 0
	v_cndmask_b32_e32 v66, v66, v67, vcc
	v_rsq_f32_e32 v66, v66
	s_nop 0
	v_mul_f32_e32 v67, 0x45800000, v66
	v_cndmask_b32_e32 v66, v66, v67, vcc
	v_pk_mul_f32 v[60:61], v[60:61], v[66:67] op_sel_hi:[1,0]
	v_pk_mul_f32 v[62:63], v[62:63], v[66:67] op_sel_hi:[1,0]
	v_pk_mul_f32 v[60:61], v[12:13], v[60:61]
	v_pk_mul_f32 v[62:63], v[14:15], v[62:63]
	v_pk_mul_f32 v[56:57], v[56:57], v[66:67] op_sel_hi:[1,0]
	v_pk_mul_f32 v[58:59], v[58:59], v[66:67] op_sel_hi:[1,0]
	global_store_dwordx4 v[68:69], v[60:63], off
	v_pk_mul_f32 v[58:59], v[10:11], v[58:59]
	v_pk_mul_f32 v[56:57], v[8:9], v[56:57]
	v_lshl_add_u64 v[60:61], v[64:65], 0, v[120:121]
	v_pk_mul_f32 v[52:53], v[52:53], v[66:67] op_sel_hi:[1,0]
	v_pk_mul_f32 v[54:55], v[54:55], v[66:67] op_sel_hi:[1,0]
	global_store_dwordx4 v[60:61], v[56:59], off
	v_pk_mul_f32 v[54:55], v[6:7], v[54:55]
	v_pk_mul_f32 v[52:53], v[4:5], v[52:53]
	v_lshl_add_u64 v[56:57], v[64:65], 0, v[116:117]
	global_store_dwordx4 v[56:57], v[52:55], off
	v_lshl_add_u64 v[56:57], v[64:65], 0, v[114:115]
	s_nop 0
	v_pk_mul_f32 v[52:53], v[154:155], v[66:67] op_sel_hi:[1,0]
	v_pk_mul_f32 v[54:55], v[152:153], v[66:67] op_sel_hi:[1,0]
	v_pk_mul_f32 v[52:53], v[0:1], v[52:53]
	v_pk_mul_f32 v[54:55], v[2:3], v[54:55]
	global_store_dwordx4 v[56:57], v[52:55], off
	s_nop 1
	v_lshl_add_u64 v[52:53], v[48:49], 2, s[4:5]
	global_load_dword v52, v[52:53], off sc1
	v_lshlrev_b64 v[48:49], 13, v[48:49]
	v_lshl_add_u64 v[48:49], s[86:87], 0, v[48:49]
	v_lshl_add_u64 v[54:55], v[48:49], 0, v[124:125]
	s_waitcnt vmcnt(0)
; #define G_BAR __builtin_amdgcn_s_barrier()
; #define FOR_AI_M _Pragma("unroll") for (int ai = 0; ai < 2; ++ai) _Pragma("unroll") for (int m = 0; m < 4; ++m)
; #define FOR_BJ_N _Pragma("unroll") for (int bj = 0; bj < 2; ++bj) _Pragma("unroll") for (int n = 0; n < 2; ++n)
; template <class Epi, class Sched>
; __device__ __forceinline__ void gemm_phase(LAS unsigned char* lds, const Sched& S, const Epi& E) {
;     ...
;         if (!has_next) break;
; #pragma unroll
;         for (int a = 0; a < 2; ++a)
; #pragma unroll
;             for (int b = 0; b < 2; ++b)
; #pragma unroll
;                 for (int m = 0; m < 4; ++m)
; #pragma unroll
;                     for (int n = 0; n < 2; ++n) acc[a][b][m][n] = (f32x4){0.f, 0.f, 0.f, 0.f};
;         cur = nxt; cA = nA; cB = nB; vc0 = vn0; vc1 = vn1; hAc = hAn; ++ui;
;         if (wr == 1) G_BAR;
;     __device__ __forceinline__ void operator()(EPI_ARGS) const {
;     ...
;         FOR_AI_M {
;             const int row = u.pm * 256 + ai * 128 + wr * 64 + m * 16 + fr;
;             const float rs = rsqrtf(__hip_atomic_load(ssq_o + row, __ATOMIC_RELAXED, __HIP_MEMORY_SCOPE_AGENT) * (1.0f / 2048.0f) + EPS);
;             FOR_BJ_N { const int col = u.pn * 256 + bj * 128 + wc * 32 + n * 16 + 4 * fq;
;                 __builtin_nontemporal_store(acc[ai][bj][m][n] * rs * gv[bj][n], (f32x4*)(out + ((size_t)row * 2048 + col))); }
	v_fmamk_f32 v52, v52, 0x3a000000, v182
	v_cmp_gt_f32_e32 vcc, s47, v52
	v_mul_f32_e32 v53, 0x4b800000, v52
	s_nop 0
	v_cndmask_b32_e32 v52, v52, v53, vcc
	v_rsq_f32_e32 v52, v52
	s_nop 0
	v_mul_f32_e32 v53, 0x45800000, v52
	v_cndmask_b32_e32 v52, v52, v53, vcc
	v_pk_mul_f32 v[44:45], v[44:45], v[52:53] op_sel_hi:[1,0]
	v_pk_mul_f32 v[46:47], v[46:47], v[52:53] op_sel_hi:[1,0]
	v_pk_mul_f32 v[44:45], v[12:13], v[44:45]
	v_pk_mul_f32 v[46:47], v[14:15], v[46:47]
	v_pk_mul_f32 v[40:41], v[40:41], v[52:53] op_sel_hi:[1,0]
	v_pk_mul_f32 v[42:43], v[42:43], v[52:53] op_sel_hi:[1,0]
	global_store_dwordx4 v[54:55], v[44:47], off
	v_pk_mul_f32 v[42:43], v[10:11], v[42:43]
	v_pk_mul_f32 v[40:41], v[8:9], v[40:41]
	v_lshl_add_u64 v[44:45], v[48:49], 0, v[120:121]
	v_pk_mul_f32 v[36:37], v[36:37], v[52:53] op_sel_hi:[1,0]
	v_pk_mul_f32 v[38:39], v[38:39], v[52:53] op_sel_hi:[1,0]
	global_store_dwordx4 v[44:45], v[40:43], off
	v_pk_mul_f32 v[38:39], v[6:7], v[38:39]
	v_pk_mul_f32 v[36:37], v[4:5], v[36:37]
	v_lshl_add_u64 v[40:41], v[48:49], 0, v[116:117]
	global_store_dwordx4 v[40:41], v[36:39], off
	v_lshl_add_u64 v[40:41], v[48:49], 0, v[114:115]
	s_nop 0
	v_pk_mul_f32 v[36:37], v[162:163], v[52:53] op_sel_hi:[1,0]
	v_pk_mul_f32 v[38:39], v[160:161], v[52:53] op_sel_hi:[1,0]
	v_pk_mul_f32 v[36:37], v[0:1], v[36:37]
	v_pk_mul_f32 v[38:39], v[2:3], v[38:39]
	global_store_dwordx4 v[40:41], v[36:39], off
	s_nop 1
	v_lshl_add_u64 v[36:37], v[32:33], 2, s[4:5]
	global_load_dword v36, v[36:37], off sc1
	v_lshlrev_b64 v[32:33], 13, v[32:33]
	v_lshl_add_u64 v[32:33], s[86:87], 0, v[32:33]
	v_lshl_add_u64 v[38:39], v[32:33], 0, v[124:125]
	s_waitcnt vmcnt(0)
	v_fmamk_f32 v36, v36, 0x3a000000, v182
	v_cmp_gt_f32_e32 vcc, s47, v36
	v_mul_f32_e32 v37, 0x4b800000, v36
	s_nop 0
	v_cndmask_b32_e32 v36, v36, v37, vcc
	v_rsq_f32_e32 v36, v36
	s_nop 0
	v_mul_f32_e32 v37, 0x45800000, v36
	v_cndmask_b32_e32 v36, v36, v37, vcc
	v_pk_mul_f32 v[28:29], v[28:29], v[36:37] op_sel_hi:[1,0]
	v_pk_mul_f32 v[30:31], v[30:31], v[36:37] op_sel_hi:[1,0]
	v_pk_mul_f32 v[28:29], v[12:13], v[28:29]
	v_pk_mul_f32 v[30:31], v[14:15], v[30:31]
	v_pk_mul_f32 v[24:25], v[24:25], v[36:37] op_sel_hi:[1,0]
	v_pk_mul_f32 v[26:27], v[26:27], v[36:37] op_sel_hi:[1,0]
	global_store_dwordx4 v[38:39], v[28:31], off
	v_pk_mul_f32 v[26:27], v[10:11], v[26:27]
	v_pk_mul_f32 v[24:25], v[8:9], v[24:25]
	v_lshl_add_u64 v[28:29], v[32:33], 0, v[120:121]
	global_store_dwordx4 v[28:29], v[24:27], off
	v_pk_mul_f32 v[22:23], v[22:23], v[36:37] op_sel_hi:[1,0]
	s_nop 0
	v_pk_mul_f32 v[26:27], v[50:51], v[36:37] op_sel_hi:[1,0]
	v_pk_mul_f32 v[24:25], v[6:7], v[22:23]
	v_pk_mul_f32 v[22:23], v[4:5], v[26:27]
	v_lshl_add_u64 v[26:27], v[32:33], 0, v[116:117]
	global_store_dwordx4 v[26:27], v[22:25], off
	v_lshl_add_u64 v[26:27], v[32:33], 0, v[114:115]
	s_nop 0
	v_pk_mul_f32 v[22:23], v[166:167], v[36:37] op_sel_hi:[1,0]
	v_pk_mul_f32 v[24:25], v[164:165], v[36:37] op_sel_hi:[1,0]
	v_pk_mul_f32 v[22:23], v[0:1], v[22:23]
	v_pk_mul_f32 v[24:25], v[2:3], v[24:25]
	global_store_dwordx4 v[26:27], v[22:25], off
	s_nop 1
	v_lshl_add_u64 v[22:23], v[16:17], 2, s[4:5]
	global_load_dword v22, v[22:23], off sc1
	v_lshlrev_b64 v[16:17], 13, v[16:17]
	v_lshl_add_u64 v[16:17], s[86:87], 0, v[16:17]
	s_waitcnt vmcnt(0)
	v_fmamk_f32 v22, v22, 0x3a000000, v182
	v_cmp_gt_f32_e32 vcc, s47, v22
	v_mul_f32_e32 v23, 0x4b800000, v22
	s_nop 0
	v_cndmask_b32_e32 v22, v22, v23, vcc
	v_rsq_f32_e32 v22, v22
	s_nop 0
	v_mul_f32_e32 v23, 0x45800000, v22
	v_cndmask_b32_e32 v22, v22, v23, vcc
	v_pk_mul_f32 v[20:21], v[20:21], v[22:23] op_sel_hi:[1,0]
	v_pk_mul_f32 v[18:19], v[18:19], v[22:23] op_sel_hi:[1,0]
	v_pk_mul_f32 v[12:13], v[12:13], v[20:21]
	v_pk_mul_f32 v[14:15], v[14:15], v[18:19]
	v_lshl_add_u64 v[18:19], v[16:17], 0, v[124:125]
	global_store_dwordx4 v[18:19], v[12:15], off
	s_andn2_b64 vcc, exec, s[24:25]
	s_nop 0
	v_pk_mul_f32 v[12:13], v[150:151], v[22:23] op_sel_hi:[1,0]
	v_pk_mul_f32 v[14:15], v[34:35], v[22:23] op_sel_hi:[1,0]
	v_pk_mul_f32 v[8:9], v[8:9], v[12:13]
	v_pk_mul_f32 v[10:11], v[10:11], v[14:15]
	v_lshl_add_u64 v[12:13], v[16:17], 0, v[120:121]
	global_store_dwordx4 v[12:13], v[8:11], off
	s_nop 1
	v_pk_mul_f32 v[8:9], v[158:159], v[22:23] op_sel_hi:[1,0]
	v_pk_mul_f32 v[10:11], v[156:157], v[22:23] op_sel_hi:[1,0]
	v_pk_mul_f32 v[4:5], v[4:5], v[8:9]
	v_pk_mul_f32 v[6:7], v[6:7], v[10:11]
	v_lshl_add_u64 v[8:9], v[16:17], 0, v[116:117]
	global_store_dwordx4 v[8:9], v[4:7], off
	s_nop 1
	v_pk_mul_f32 v[4:5], v[176:177], v[22:23] op_sel_hi:[1,0]
	v_pk_mul_f32 v[6:7], v[168:169], v[22:23] op_sel_hi:[1,0]
	v_pk_mul_f32 v[0:1], v[0:1], v[4:5]
	v_pk_mul_f32 v[2:3], v[2:3], v[6:7]
	v_lshl_add_u64 v[4:5], v[16:17], 0, v[114:115]
	global_store_dwordx4 v[4:5], v[0:3], off
	s_cbranch_vccnz .LBB0_1301
	s_andn2_b64 vcc, exec, s[18:19]
	s_cbranch_vccnz .LBB0_1300
	s_barrier
	s_branch .LBB0_1300
